# attention epilogues: half-row dwordx2 stores widened to dwordx4 with a v_permlane32_swap exchange between the half-waves
# speedup vs baseline: 1.0077x; 1.0077x over previous
.LBB0_431:
	v_sub_f32_e32 v33, v164, v72
	v_exp_f32_e32 v33, v33
	s_waitcnt lgkmcnt(0)
	v_add_f32_e32 v32, v74, v32
	v_add_f32_e32 v34, v32, v33
	v_div_scale_f32 v35, s[0:1], v34, v34, 1.0
	v_rcp_f32_e32 v36, v35
	v_div_scale_f32 v37, vcc, 1.0, v34, 1.0
	v_lshl_add_u64 v[32:33], v[194:195], 1, v[154:155]
	v_fma_f32 v38, -v35, v36, 1.0
	v_fmac_f32_e32 v36, v38, v36
	v_mul_f32_e32 v38, v37, v36
	v_fma_f32 v39, -v35, v38, v37
	v_fmac_f32_e32 v38, v39, v36
	v_fma_f32 v35, -v35, v38, v37
	v_div_fmas_f32 v35, v35, v36, v38
	v_div_fixup_f32 v34, v35, v34, 1.0
	v_pk_mul_f32 v[0:1], v[0:1], v[34:35] op_sel_hi:[1,0]
	v_pk_mul_f32 v[2:3], v[2:3], v[34:35] op_sel_hi:[1,0]
	v_pk_mul_f32 v[4:5], v[4:5], v[34:35] op_sel_hi:[1,0]
	v_pk_mul_f32 v[6:7], v[6:7], v[34:35] op_sel_hi:[1,0]
	v_pk_mul_f32 v[8:9], v[8:9], v[34:35] op_sel_hi:[1,0]
	v_pk_mul_f32 v[10:11], v[10:11], v[34:35] op_sel_hi:[1,0]
	v_pk_mul_f32 v[12:13], v[12:13], v[34:35] op_sel_hi:[1,0]
	v_pk_mul_f32 v[14:15], v[14:15], v[34:35] op_sel_hi:[1,0]
	v_pk_mul_f32 v[16:17], v[16:17], v[34:35] op_sel_hi:[1,0]
	v_pk_mul_f32 v[18:19], v[18:19], v[34:35] op_sel_hi:[1,0]
	v_pk_mul_f32 v[20:21], v[20:21], v[34:35] op_sel_hi:[1,0]
	v_pk_mul_f32 v[22:23], v[22:23], v[34:35] op_sel_hi:[1,0]
	v_pk_mul_f32 v[24:25], v[24:25], v[34:35] op_sel_hi:[1,0]
	v_pk_mul_f32 v[26:27], v[26:27], v[34:35] op_sel_hi:[1,0]
	v_pk_mul_f32 v[28:29], v[28:29], v[34:35] op_sel_hi:[1,0]
	v_pk_mul_f32 v[30:31], v[30:31], v[34:35] op_sel_hi:[1,0]
	v_mbcnt_lo_u32_b32 v36, -1, 0
	v_mbcnt_hi_u32_b32 v36, -1, v36
	v_and_b32_e32 v36, 32, v36
	v_lshrrev_b32_e32 v36, 2, v36
	v_mov_b32_e32 v37, 0
	v_lshl_add_u64 v[32:33], v[32:33], 0, v[36:37]
	v_cvt_pk_bf16_f32 v0, v0, v1
	v_cvt_pk_bf16_f32 v1, v2, v3
	v_cvt_pk_bf16_f32 v2, v4, v5
	v_cvt_pk_bf16_f32 v3, v6, v7
	v_cvt_pk_bf16_f32 v4, v8, v9
	v_cvt_pk_bf16_f32 v5, v10, v11
	v_cvt_pk_bf16_f32 v6, v12, v13
	v_cvt_pk_bf16_f32 v7, v14, v15
	v_cvt_pk_bf16_f32 v8, v16, v17
	v_cvt_pk_bf16_f32 v9, v18, v19
	v_cvt_pk_bf16_f32 v10, v20, v21
	v_cvt_pk_bf16_f32 v11, v22, v23
	v_cvt_pk_bf16_f32 v12, v24, v25
	v_cvt_pk_bf16_f32 v13, v26, v27
	v_cvt_pk_bf16_f32 v14, v28, v29
	v_cvt_pk_bf16_f32 v15, v30, v31
	s_nop 1
	v_permlane32_swap_b32_e32 v0, v2
	v_permlane32_swap_b32_e32 v1, v3
	v_permlane32_swap_b32_e32 v4, v6
	v_permlane32_swap_b32_e32 v5, v7
	v_permlane32_swap_b32_e32 v8, v10
	v_permlane32_swap_b32_e32 v9, v11
	v_permlane32_swap_b32_e32 v12, v14
	v_permlane32_swap_b32_e32 v13, v15
	global_store_dwordx4 v[32:33], v[0:3], off
	global_store_dwordx4 v[32:33], v[4:7], off offset:32
	global_store_dwordx4 v[32:33], v[8:11], off offset:64
	global_store_dwordx4 v[32:33], v[12:15], off offset:96

.LBB0_984:
	s_and_saveexec_b64 s[4:5], s[0:1]
	s_cbranch_execz .LBB0_952
	v_readlane_b32 s0, v254, 0
	v_readlane_b32 s1, v254, 1
	v_bfe_u32 v147, v6, 5, 1
	v_bfe_u32 v2, v6, 2, 2
	v_lshl_add_u64 v[144:145], v[0:1], 1, s[0:1]
	v_mul_u32_u24_e32 v0, 0x90, v7
	v_lshlrev_b32_e32 v1, 4, v147
	v_lshl_or_b32 v2, v147, 2, v2
	v_lshlrev_b32_e32 v3, 1, v6
	v_lshlrev_b32_e32 v4, 3, v6
	v_and_b32_e32 v3, 32, v3
	v_and_b32_e32 v4, 24, v4
	v_add3_u32 v151, 0, v0, v1
	v_mad_u32_u24 v0, v2, s21, 0
	v_and_b32_e32 v1, 64, v197
	v_add3_u32 v150, v0, v3, v4
	v_xor_b32_e32 v0, 32, v197
	v_add_u32_e32 v1, 64, v1
	v_cmp_lt_i32_e32 vcc, v0, v1
	s_mov_b32 s0, 0xff61b1e6
	v_add_u32_e32 v149, 0x9000, v150
	v_cndmask_b32_e32 v0, v197, v0, vcc
	v_lshlrev_b32_e32 v148, 2, v0
	ds_read_b128 v[0:3], v151
	ds_read_b128 v[4:7], v151 offset:32
	s_waitcnt vmcnt(3) lgkmcnt(1)
	v_mfma_f32_32x32x16_bf16 v[48:63], v[0:3], v[116:119], 0
	ds_read_b128 v[0:3], v151 offset:64
	ds_read_b128 v[64:67], v151 offset:13856
	s_waitcnt vmcnt(2) lgkmcnt(2)
	v_mfma_f32_32x32x16_bf16 v[48:63], v[4:7], v[120:123], v[48:63]
	s_waitcnt vmcnt(1) lgkmcnt(1)
	v_mfma_f32_32x32x16_bf16 v[48:63], v[0:3], v[124:127], v[48:63]
	ds_read_b128 v[0:3], v151 offset:96
	s_waitcnt vmcnt(0) lgkmcnt(0)
	v_mfma_f32_32x32x16_bf16 v[48:63], v[0:3], v[128:131], v[48:63]
	ds_read_b128 v[0:3], v151 offset:4608
	s_waitcnt lgkmcnt(0)
	v_mfma_f32_32x32x16_bf16 v[32:47], v[0:3], v[116:119], 0
	ds_read_b128 v[0:3], v151 offset:4640
	s_waitcnt lgkmcnt(0)
	v_mfma_f32_32x32x16_bf16 v[32:47], v[0:3], v[120:123], v[32:47]
	ds_read_b128 v[0:3], v151 offset:4672
	s_waitcnt lgkmcnt(0)
	v_mfma_f32_32x32x16_bf16 v[32:47], v[0:3], v[124:127], v[32:47]
	ds_read_b128 v[0:3], v151 offset:4704
	s_waitcnt lgkmcnt(0)
	v_mfma_f32_32x32x16_bf16 v[32:47], v[0:3], v[128:131], v[32:47]
	ds_read_b128 v[0:3], v151 offset:9216
	s_waitcnt lgkmcnt(0)
	v_mfma_f32_32x32x16_bf16 v[16:31], v[0:3], v[116:119], 0
	ds_read_b128 v[0:3], v151 offset:9248
	s_waitcnt lgkmcnt(0)
	v_mfma_f32_32x32x16_bf16 v[16:31], v[0:3], v[120:123], v[16:31]
	ds_read_b128 v[0:3], v151 offset:9280
	s_waitcnt lgkmcnt(0)
	v_mfma_f32_32x32x16_bf16 v[16:31], v[0:3], v[124:127], v[16:31]
	ds_read_b128 v[0:3], v151 offset:9312
	s_waitcnt lgkmcnt(0)
	v_mfma_f32_32x32x16_bf16 v[16:31], v[0:3], v[128:131], v[16:31]
	ds_read_b128 v[0:3], v151 offset:13824
	s_waitcnt lgkmcnt(0)
	v_mfma_f32_32x32x16_bf16 v[0:15], v[0:3], v[116:119], 0
	v_mfma_f32_32x32x16_bf16 v[0:15], v[64:67], v[120:123], v[0:15]
	ds_read_b128 v[64:67], v151 offset:13888
	s_waitcnt lgkmcnt(0)
	v_mfma_f32_32x32x16_bf16 v[0:15], v[64:67], v[124:127], v[0:15]
	ds_read_b128 v[64:67], v151 offset:13920
	s_waitcnt lgkmcnt(0)
	v_mfma_f32_32x32x16_bf16 v[0:15], v[64:67], v[128:131], v[0:15]
	v_mul_f32_e32 v64, 0x3e38aa3b, v48
	v_mul_f32_e32 v65, 0x3e38aa3b, v49
	v_max3_f32 v64, v64, s0, v65
	v_mul_f32_e32 v65, 0x3e38aa3b, v50
	v_mul_f32_e32 v66, 0x3e38aa3b, v51
	v_max3_f32 v64, v64, v65, v66
	v_mul_f32_e32 v65, 0x3e38aa3b, v52
	v_mul_f32_e32 v66, 0x3e38aa3b, v53
	v_max3_f32 v64, v64, v65, v66
	v_mul_f32_e32 v65, 0x3e38aa3b, v54
	v_mul_f32_e32 v66, 0x3e38aa3b, v55
	v_max3_f32 v64, v64, v65, v66
	v_mul_f32_e32 v65, 0x3e38aa3b, v56
	v_mul_f32_e32 v66, 0x3e38aa3b, v57
	v_max3_f32 v64, v64, v65, v66
	v_mul_f32_e32 v65, 0x3e38aa3b, v58
	v_mul_f32_e32 v66, 0x3e38aa3b, v59
	v_max3_f32 v64, v64, v65, v66
	v_mul_f32_e32 v65, 0x3e38aa3b, v60
	v_mul_f32_e32 v66, 0x3e38aa3b, v61
	v_max3_f32 v64, v64, v65, v66
	v_mul_f32_e32 v65, 0x3e38aa3b, v62
	v_mul_f32_e32 v66, 0x3e38aa3b, v63
	v_max3_f32 v64, v64, v65, v66
	v_mul_f32_e32 v65, 0x3e38aa3b, v32
	v_mul_f32_e32 v66, 0x3e38aa3b, v33
	v_max3_f32 v64, v64, v65, v66
	v_mul_f32_e32 v65, 0x3e38aa3b, v34
	v_mul_f32_e32 v66, 0x3e38aa3b, v35
	v_max3_f32 v64, v64, v65, v66
	v_mul_f32_e32 v65, 0x3e38aa3b, v36
	v_mul_f32_e32 v66, 0x3e38aa3b, v37
	v_max3_f32 v64, v64, v65, v66
	v_mul_f32_e32 v65, 0x3e38aa3b, v38
	v_mul_f32_e32 v66, 0x3e38aa3b, v39
	v_max3_f32 v64, v64, v65, v66
	v_mul_f32_e32 v65, 0x3e38aa3b, v40
	v_mul_f32_e32 v66, 0x3e38aa3b, v41
	v_max3_f32 v64, v64, v65, v66
	v_mul_f32_e32 v65, 0x3e38aa3b, v42
	v_mul_f32_e32 v66, 0x3e38aa3b, v43
	v_max3_f32 v64, v64, v65, v66
	v_mul_f32_e32 v65, 0x3e38aa3b, v44
	v_mul_f32_e32 v66, 0x3e38aa3b, v45
	v_max3_f32 v64, v64, v65, v66
	v_mul_f32_e32 v65, 0x3e38aa3b, v46
	v_mul_f32_e32 v66, 0x3e38aa3b, v47
	v_max3_f32 v64, v64, v65, v66
	v_mul_f32_e32 v65, 0x3e38aa3b, v16
	v_mul_f32_e32 v66, 0x3e38aa3b, v17
	v_max3_f32 v64, v64, v65, v66
	v_mul_f32_e32 v65, 0x3e38aa3b, v18
	v_mul_f32_e32 v66, 0x3e38aa3b, v19
	v_max3_f32 v64, v64, v65, v66
	v_mul_f32_e32 v65, 0x3e38aa3b, v20
	v_mul_f32_e32 v66, 0x3e38aa3b, v21
	v_max3_f32 v64, v64, v65, v66
	v_mul_f32_e32 v65, 0x3e38aa3b, v22
	v_mul_f32_e32 v66, 0x3e38aa3b, v23
	v_max3_f32 v64, v64, v65, v66
	v_mul_f32_e32 v65, 0x3e38aa3b, v24
	v_mul_f32_e32 v66, 0x3e38aa3b, v25
	v_max3_f32 v64, v64, v65, v66
	v_mul_f32_e32 v65, 0x3e38aa3b, v26
	v_mul_f32_e32 v66, 0x3e38aa3b, v27
	v_max3_f32 v64, v64, v65, v66
	v_mul_f32_e32 v65, 0x3e38aa3b, v28
	v_mul_f32_e32 v66, 0x3e38aa3b, v29
	v_max3_f32 v64, v64, v65, v66
	v_mul_f32_e32 v65, 0x3e38aa3b, v30
	v_mul_f32_e32 v66, 0x3e38aa3b, v31
	v_max3_f32 v64, v64, v65, v66
	v_mul_f32_e32 v65, 0x3e38aa3b, v0
	v_mul_f32_e32 v66, 0x3e38aa3b, v1
	v_max3_f32 v64, v64, v65, v66
	v_mul_f32_e32 v65, 0x3e38aa3b, v2
	v_mul_f32_e32 v66, 0x3e38aa3b, v3
	v_max3_f32 v64, v64, v65, v66
	v_mul_f32_e32 v65, 0x3e38aa3b, v4
	v_mul_f32_e32 v66, 0x3e38aa3b, v5
	v_max3_f32 v64, v64, v65, v66
	v_mul_f32_e32 v65, 0x3e38aa3b, v6
	v_mul_f32_e32 v66, 0x3e38aa3b, v7
	v_max3_f32 v64, v64, v65, v66
	v_mul_f32_e32 v65, 0x3e38aa3b, v8
	v_mul_f32_e32 v66, 0x3e38aa3b, v9
	v_max3_f32 v64, v64, v65, v66
	v_mul_f32_e32 v65, 0x3e38aa3b, v10
	v_mul_f32_e32 v66, 0x3e38aa3b, v11
	v_max3_f32 v64, v64, v65, v66
	v_mul_f32_e32 v65, 0x3e38aa3b, v12
	v_mul_f32_e32 v66, 0x3e38aa3b, v13
	v_max3_f32 v64, v64, v65, v66
	v_mul_f32_e32 v65, 0x3e38aa3b, v14
	v_mul_f32_e32 v66, 0x3e38aa3b, v15
	v_max3_f32 v64, v64, v65, v66
	ds_bpermute_b32 v65, v148, v64
	s_waitcnt lgkmcnt(0)
	v_max_f32_e32 v65, v65, v65
	v_max_f32_e32 v152, v64, v65
	v_fma_f32 v0, v0, s46, -v152
	v_fma_f32 v16, v16, s46, -v152
	v_exp_f32_e32 v224, v0
	v_fma_f32 v0, v1, s46, -v152
	v_exp_f32_e32 v185, v16
	v_fma_f32 v16, v17, s46, -v152
	v_exp_f32_e32 v225, v0
	v_fma_f32 v0, v2, s46, -v152
	v_exp_f32_e32 v186, v16
	v_fma_f32 v16, v18, s46, -v152
	v_exp_f32_e32 v226, v0
	v_fma_f32 v0, v3, s46, -v152
	v_fma_f32 v48, v48, s46, -v152
	v_exp_f32_e32 v187, v16
	v_fma_f32 v16, v19, s46, -v152
	v_exp_f32_e32 v227, v0
	v_fma_f32 v0, v4, s46, -v152
	v_exp_f32_e32 v153, v48
	v_fma_f32 v48, v49, s46, -v152
	v_exp_f32_e32 v188, v16
	v_fma_f32 v16, v20, s46, -v152
	v_exp_f32_e32 v228, v0
	v_fma_f32 v0, v5, s46, -v152
	v_exp_f32_e32 v154, v48
	v_fma_f32 v48, v50, s46, -v152
	v_exp_f32_e32 v189, v16
	v_fma_f32 v16, v21, s46, -v152
	v_exp_f32_e32 v229, v0
	v_fma_f32 v0, v6, s46, -v152
	v_exp_f32_e32 v155, v48
	v_fma_f32 v48, v51, s46, -v152
	v_exp_f32_e32 v190, v16
	v_fma_f32 v16, v22, s46, -v152
	v_exp_f32_e32 v230, v0
	v_fma_f32 v0, v7, s46, -v152
	v_exp_f32_e32 v156, v48
	v_fma_f32 v48, v52, s46, -v152
	v_fma_f32 v32, v32, s46, -v152
	v_exp_f32_e32 v191, v16
	v_fma_f32 v16, v23, s46, -v152
	v_exp_f32_e32 v231, v0
	v_fma_f32 v0, v8, s46, -v152
	v_exp_f32_e32 v157, v48
	v_fma_f32 v48, v53, s46, -v152
	v_exp_f32_e32 v169, v32
	v_fma_f32 v32, v33, s46, -v152
	v_exp_f32_e32 v194, v16
	v_fma_f32 v16, v24, s46, -v152
	v_exp_f32_e32 v232, v0
	v_fma_f32 v0, v9, s46, -v152
	v_exp_f32_e32 v158, v48
	v_fma_f32 v48, v54, s46, -v152
	v_exp_f32_e32 v170, v32
	v_fma_f32 v32, v34, s46, -v152
	v_exp_f32_e32 v202, v16
	v_fma_f32 v16, v25, s46, -v152
	v_exp_f32_e32 v233, v0
	v_fma_f32 v0, v10, s46, -v152
	v_exp_f32_e32 v159, v48
	v_fma_f32 v48, v55, s46, -v152
	v_exp_f32_e32 v171, v32
	v_fma_f32 v32, v35, s46, -v152
	v_exp_f32_e32 v205, v16
	v_fma_f32 v16, v26, s46, -v152
	v_exp_f32_e32 v234, v0
	v_fma_f32 v0, v11, s46, -v152
	v_exp_f32_e32 v160, v48
	v_fma_f32 v48, v56, s46, -v152
	v_exp_f32_e32 v172, v32
	v_fma_f32 v32, v36, s46, -v152
	v_exp_f32_e32 v218, v16
	v_fma_f32 v16, v27, s46, -v152
	v_exp_f32_e32 v235, v0
	v_fma_f32 v0, v12, s46, -v152
	ds_read_b64_tr_b16 v[4:5], v150 offset:36864
	ds_read_b64_tr_b16 v[6:7], v150 offset:38400
	v_exp_f32_e32 v161, v48
	v_fma_f32 v48, v57, s46, -v152
	v_exp_f32_e32 v173, v32
	v_fma_f32 v32, v37, s46, -v152
	v_exp_f32_e32 v219, v16
	v_fma_f32 v16, v28, s46, -v152
	v_exp_f32_e32 v236, v0
	v_fma_f32 v0, v13, s46, -v152
	v_exp_f32_e32 v162, v48
	v_fma_f32 v48, v58, s46, -v152
	v_exp_f32_e32 v174, v32
	v_fma_f32 v32, v38, s46, -v152
	v_exp_f32_e32 v220, v16
	v_fma_f32 v16, v29, s46, -v152
	v_exp_f32_e32 v237, v0
	v_fma_f32 v0, v14, s46, -v152
	v_exp_f32_e32 v163, v48
	v_fma_f32 v48, v59, s46, -v152
	v_exp_f32_e32 v175, v32
	v_fma_f32 v32, v39, s46, -v152
	v_exp_f32_e32 v221, v16
	v_fma_f32 v16, v30, s46, -v152
	v_exp_f32_e32 v238, v0
	v_fma_f32 v0, v15, s46, -v152
	v_exp_f32_e32 v164, v48
	v_fma_f32 v48, v60, s46, -v152
	v_exp_f32_e32 v176, v32
	v_fma_f32 v32, v40, s46, -v152
	v_exp_f32_e32 v222, v16
	v_fma_f32 v16, v31, s46, -v152
	v_exp_f32_e32 v239, v0
	v_cvt_pk_bf16_f32 v0, v153, v154
	v_cvt_pk_bf16_f32 v1, v155, v156
	v_cvt_pk_bf16_f32 v2, v157, v158
	v_cvt_pk_bf16_f32 v3, v159, v160
	v_exp_f32_e32 v165, v48
	v_fma_f32 v48, v61, s46, -v152
	v_exp_f32_e32 v177, v32
	v_fma_f32 v32, v41, s46, -v152
	v_exp_f32_e32 v223, v16
	s_waitcnt lgkmcnt(0)
	v_mfma_f32_32x32x16_bf16 v[16:31], v[4:7], v[0:3], 0
	ds_read_b64_tr_b16 v[4:5], v150 offset:36928
	ds_read_b64_tr_b16 v[6:7], v150 offset:38464
	v_exp_f32_e32 v166, v48
	v_fma_f32 v48, v62, s46, -v152
	v_exp_f32_e32 v178, v32
	v_fma_f32 v32, v42, s46, -v152
	v_exp_f32_e32 v167, v48
	v_fma_f32 v48, v63, s46, -v152
	v_exp_f32_e32 v179, v32
	v_fma_f32 v32, v43, s46, -v152
	v_exp_f32_e32 v168, v48
	v_exp_f32_e32 v180, v32
	v_fma_f32 v32, v44, s46, -v152
	ds_read_b64_tr_b16 v[36:37], v150 offset:39936
	ds_read_b64_tr_b16 v[38:39], v150 offset:41472
	v_exp_f32_e32 v181, v32
	v_fma_f32 v32, v45, s46, -v152
	v_exp_f32_e32 v182, v32
	v_fma_f32 v32, v46, s46, -v152
	s_waitcnt lgkmcnt(2)
	v_mfma_f32_32x32x16_bf16 v[0:15], v[4:7], v[0:3], 0
	v_exp_f32_e32 v183, v32
	v_fma_f32 v32, v47, s46, -v152
	v_exp_f32_e32 v184, v32
	v_cvt_pk_bf16_f32 v32, v161, v162
	v_cvt_pk_bf16_f32 v33, v163, v164
	v_cvt_pk_bf16_f32 v34, v165, v166
	v_cvt_pk_bf16_f32 v35, v167, v168
	v_add_f32_e32 v153, 0, v153
	v_add_f32_e32 v153, v154, v153
	s_waitcnt lgkmcnt(0)
	v_mfma_f32_32x32x16_bf16 v[16:31], v[36:39], v[32:35], v[16:31]
	ds_read_b64_tr_b16 v[36:37], v150 offset:40000
	ds_read_b64_tr_b16 v[38:39], v150 offset:41536
	v_add_f32_e32 v153, v155, v153
	v_add_f32_e32 v153, v156, v153
	v_add_f32_e32 v153, v157, v153
	v_add_f32_e32 v153, v158, v153
	v_add_f32_e32 v153, v159, v153
	v_add_f32_e32 v153, v160, v153
	s_waitcnt lgkmcnt(0)
	v_mfma_f32_32x32x16_bf16 v[0:15], v[36:39], v[32:35], v[0:15]
	ds_read_b64_tr_b16 v[36:37], v150 offset:43008
	ds_read_b64_tr_b16 v[38:39], v150 offset:44544
	v_cvt_pk_bf16_f32 v32, v169, v170
	v_cvt_pk_bf16_f32 v33, v171, v172
	v_cvt_pk_bf16_f32 v34, v173, v174
	v_cvt_pk_bf16_f32 v35, v175, v176
	v_add_f32_e32 v153, v161, v153
	v_add_f32_e32 v153, v162, v153
	s_waitcnt lgkmcnt(0)
	v_mfma_f32_32x32x16_bf16 v[16:31], v[36:39], v[32:35], v[16:31]
	ds_read_b64_tr_b16 v[36:37], v150 offset:43072
	ds_read_b64_tr_b16 v[38:39], v150 offset:44608
	v_add_f32_e32 v153, v163, v153
	v_add_f32_e32 v153, v164, v153
	v_add_f32_e32 v153, v165, v153
	v_add_f32_e32 v153, v166, v153
	v_add_f32_e32 v153, v167, v153
	v_add_f32_e32 v153, v168, v153
	s_waitcnt lgkmcnt(0)
	v_mfma_f32_32x32x16_bf16 v[0:15], v[36:39], v[32:35], v[0:15]
	ds_read_b64_tr_b16 v[36:37], v150 offset:46080
	ds_read_b64_tr_b16 v[38:39], v150 offset:47616
	v_cvt_pk_bf16_f32 v32, v177, v178
	v_cvt_pk_bf16_f32 v33, v179, v180
	v_cvt_pk_bf16_f32 v34, v181, v182
	v_cvt_pk_bf16_f32 v35, v183, v184
	v_add_f32_e32 v153, v169, v153
	v_add_f32_e32 v153, v170, v153
	s_waitcnt lgkmcnt(0)
	v_mfma_f32_32x32x16_bf16 v[16:31], v[36:39], v[32:35], v[16:31]
	ds_read_b64_tr_b16 v[36:37], v150 offset:46144
	ds_read_b64_tr_b16 v[38:39], v150 offset:47680
	v_add_f32_e32 v153, v171, v153
	v_add_f32_e32 v153, v172, v153
	v_add_f32_e32 v153, v173, v153
	v_add_f32_e32 v153, v174, v153
	v_add_f32_e32 v153, v175, v153
	v_add_f32_e32 v153, v176, v153
	s_waitcnt lgkmcnt(0)
	v_mfma_f32_32x32x16_bf16 v[0:15], v[36:39], v[32:35], v[0:15]
	ds_read_b64_tr_b16 v[36:37], v150 offset:49152
	ds_read_b64_tr_b16 v[38:39], v150 offset:50688
	v_cvt_pk_bf16_f32 v32, v185, v186
	v_cvt_pk_bf16_f32 v33, v187, v188
	v_cvt_pk_bf16_f32 v34, v189, v190
	v_cvt_pk_bf16_f32 v35, v191, v194
	v_add_f32_e32 v153, v177, v153
	v_add_f32_e32 v153, v178, v153
	s_waitcnt lgkmcnt(0)
	v_mfma_f32_32x32x16_bf16 v[16:31], v[36:39], v[32:35], v[16:31]
	ds_read_b64_tr_b16 v[36:37], v150 offset:49216
	ds_read_b64_tr_b16 v[38:39], v150 offset:50752
	v_add_f32_e32 v153, v179, v153
	v_add_f32_e32 v153, v180, v153
	v_add_f32_e32 v153, v181, v153
	v_add_f32_e32 v153, v182, v153
	v_add_f32_e32 v153, v183, v153
	v_add_f32_e32 v153, v184, v153
	s_waitcnt lgkmcnt(0)
	v_mfma_f32_32x32x16_bf16 v[0:15], v[36:39], v[32:35], v[0:15]
	ds_read_b64_tr_b16 v[36:37], v150 offset:52224
	ds_read_b64_tr_b16 v[38:39], v150 offset:53760
	v_cvt_pk_bf16_f32 v32, v202, v205
	v_cvt_pk_bf16_f32 v33, v218, v219
	v_cvt_pk_bf16_f32 v34, v220, v221
	v_cvt_pk_bf16_f32 v35, v222, v223
	v_add_f32_e32 v153, v185, v153
	v_add_f32_e32 v153, v186, v153
	s_waitcnt lgkmcnt(0)
	v_mfma_f32_32x32x16_bf16 v[16:31], v[36:39], v[32:35], v[16:31]
	ds_read_b64_tr_b16 v[36:37], v150 offset:52288
	ds_read_b64_tr_b16 v[38:39], v150 offset:53824
	v_add_f32_e32 v153, v187, v153
	v_add_f32_e32 v153, v188, v153
	v_add_f32_e32 v153, v189, v153
	v_add_f32_e32 v153, v190, v153
	v_add_f32_e32 v153, v191, v153
	v_add_f32_e32 v153, v194, v153
	s_waitcnt lgkmcnt(0)
	v_mfma_f32_32x32x16_bf16 v[0:15], v[36:39], v[32:35], v[0:15]
	ds_read_b64_tr_b16 v[36:37], v150 offset:55296
	ds_read_b64_tr_b16 v[38:39], v150 offset:56832
	v_cvt_pk_bf16_f32 v32, v224, v225
	v_cvt_pk_bf16_f32 v33, v226, v227
	v_cvt_pk_bf16_f32 v34, v228, v229
	v_cvt_pk_bf16_f32 v35, v230, v231
	v_add_f32_e32 v153, v202, v153
	v_add_f32_e32 v153, v205, v153
	s_waitcnt lgkmcnt(0)
	v_mfma_f32_32x32x16_bf16 v[16:31], v[36:39], v[32:35], v[16:31]
	ds_read_b64_tr_b16 v[36:37], v150 offset:55360
	ds_read_b64_tr_b16 v[38:39], v150 offset:56896
	v_add_f32_e32 v153, v218, v153
	v_add_f32_e32 v153, v219, v153
	v_add_f32_e32 v153, v220, v153
	v_add_f32_e32 v153, v221, v153
	v_add_f32_e32 v153, v222, v153
	v_add_f32_e32 v153, v223, v153
	s_waitcnt lgkmcnt(0)
	v_mfma_f32_32x32x16_bf16 v[0:15], v[36:39], v[32:35], v[0:15]
	ds_read_b64_tr_b16 v[36:37], v150 offset:58368
	ds_read_b64_tr_b16 v[38:39], v150 offset:59904
	v_cvt_pk_bf16_f32 v32, v232, v233
	v_cvt_pk_bf16_f32 v33, v234, v235
	v_cvt_pk_bf16_f32 v34, v236, v237
	v_cvt_pk_bf16_f32 v35, v238, v239
	v_add_f32_e32 v153, v224, v153
	v_add_f32_e32 v153, v225, v153
	s_waitcnt lgkmcnt(0)
	v_mfma_f32_32x32x16_bf16 v[16:31], v[36:39], v[32:35], v[16:31]
	ds_read_b64_tr_b16 v[36:37], v150 offset:58432
	ds_read_b64_tr_b16 v[38:39], v150 offset:59968
	ds_read_b128 v[198:201], v151 offset:32288
	v_add_f32_e32 v153, v226, v153
	v_add_f32_e32 v153, v227, v153
	v_add_f32_e32 v153, v228, v153
	v_add_f32_e32 v153, v229, v153
	v_add_f32_e32 v153, v230, v153
	s_waitcnt lgkmcnt(1)
	v_mfma_f32_32x32x16_bf16 v[0:15], v[36:39], v[32:35], v[0:15]
	ds_read_b128 v[32:35], v151 offset:18432
	v_add_f32_e32 v153, v231, v153
	v_add_f32_e32 v153, v232, v153
	v_add_f32_e32 v153, v233, v153
	v_add_f32_e32 v153, v234, v153
	v_add_f32_e32 v153, v235, v153
	v_add_f32_e32 v153, v236, v153
	s_waitcnt lgkmcnt(0)
	v_mfma_f32_32x32x16_bf16 v[80:95], v[32:35], v[116:119], 0
	ds_read_b128 v[32:35], v151 offset:18464
	v_add_f32_e32 v153, v237, v153
	v_add_f32_e32 v153, v238, v153
	v_add_f32_e32 v153, v239, v153
	v_lshlrev_b32_e32 v194, 3, v147
	s_waitcnt lgkmcnt(0)
	v_mfma_f32_32x32x16_bf16 v[80:95], v[32:35], v[120:123], v[80:95]
	ds_read_b128 v[32:35], v151 offset:18496
	s_waitcnt lgkmcnt(0)
	v_mfma_f32_32x32x16_bf16 v[80:95], v[32:35], v[124:127], v[80:95]
	ds_read_b128 v[32:35], v151 offset:18528
	s_waitcnt lgkmcnt(0)
	v_mfma_f32_32x32x16_bf16 v[80:95], v[32:35], v[128:131], v[80:95]
	ds_read_b128 v[32:35], v151 offset:23040
	s_waitcnt lgkmcnt(0)
	v_mfma_f32_32x32x16_bf16 v[64:79], v[32:35], v[116:119], 0
	ds_read_b128 v[32:35], v151 offset:23072
	s_nop 7
	v_mul_f32_e32 v192, 0x3e38aa3b, v81
	s_waitcnt lgkmcnt(0)
	v_mfma_f32_32x32x16_bf16 v[64:79], v[32:35], v[120:123], v[64:79]
	ds_read_b128 v[32:35], v151 offset:23104
	s_waitcnt lgkmcnt(0)
	v_mfma_f32_32x32x16_bf16 v[64:79], v[32:35], v[124:127], v[64:79]
	ds_read_b128 v[32:35], v151 offset:23136
	s_waitcnt lgkmcnt(0)
	v_mfma_f32_32x32x16_bf16 v[64:79], v[32:35], v[128:131], v[64:79]
	ds_read_b128 v[32:35], v151 offset:27648
	s_waitcnt lgkmcnt(0)
	v_mfma_f32_32x32x16_bf16 v[48:63], v[32:35], v[116:119], 0
	ds_read_b128 v[32:35], v151 offset:27680
	s_waitcnt lgkmcnt(0)
	v_mfma_f32_32x32x16_bf16 v[48:63], v[32:35], v[120:123], v[48:63]
	ds_read_b128 v[32:35], v151 offset:27712
	s_waitcnt lgkmcnt(0)
	v_mfma_f32_32x32x16_bf16 v[48:63], v[32:35], v[124:127], v[48:63]
	ds_read_b128 v[32:35], v151 offset:27744
	s_waitcnt lgkmcnt(0)
	v_mfma_f32_32x32x16_bf16 v[48:63], v[32:35], v[128:131], v[48:63]
	ds_read_b128 v[32:35], v151 offset:32256
	s_waitcnt lgkmcnt(0)
	v_mfma_f32_32x32x16_bf16 v[32:47], v[32:35], v[116:119], 0
	v_mfma_f32_32x32x16_bf16 v[32:47], v[198:201], v[120:123], v[32:47]
	ds_read_b128 v[198:201], v151 offset:32320
	s_waitcnt lgkmcnt(0)
	v_mfma_f32_32x32x16_bf16 v[32:47], v[198:201], v[124:127], v[32:47]
	ds_read_b128 v[198:201], v151 offset:32352
	v_mul_f32_e32 v151, 0x3e38aa3b, v80
	v_max3_f32 v151, v152, v151, v192
	v_mul_f32_e32 v192, 0x3e38aa3b, v82
	s_waitcnt lgkmcnt(0)
	v_mfma_f32_32x32x16_bf16 v[32:47], v[198:201], v[128:131], v[32:47]
	v_mul_f32_e32 v198, 0x3e38aa3b, v83
	v_max3_f32 v151, v151, v192, v198
	v_mul_f32_e32 v192, 0x3e38aa3b, v84
	v_mul_f32_e32 v198, 0x3e38aa3b, v85
	v_max3_f32 v151, v151, v192, v198
	v_mul_f32_e32 v192, 0x3e38aa3b, v86
	v_mul_f32_e32 v198, 0x3e38aa3b, v87
	v_max3_f32 v151, v151, v192, v198
	v_mul_f32_e32 v192, 0x3e38aa3b, v88
	v_mul_f32_e32 v198, 0x3e38aa3b, v89
	v_max3_f32 v151, v151, v192, v198
	v_mul_f32_e32 v192, 0x3e38aa3b, v90
	v_mul_f32_e32 v198, 0x3e38aa3b, v91
	v_max3_f32 v151, v151, v192, v198
	v_mul_f32_e32 v192, 0x3e38aa3b, v92
	v_mul_f32_e32 v198, 0x3e38aa3b, v93
	v_max3_f32 v151, v151, v192, v198
	v_mul_f32_e32 v192, 0x3e38aa3b, v94
	v_mul_f32_e32 v198, 0x3e38aa3b, v95
	v_max3_f32 v151, v151, v192, v198
	v_mul_f32_e32 v192, 0x3e38aa3b, v64
	v_mul_f32_e32 v198, 0x3e38aa3b, v65
	v_max3_f32 v151, v151, v192, v198
	v_mul_f32_e32 v192, 0x3e38aa3b, v66
	v_mul_f32_e32 v198, 0x3e38aa3b, v67
	v_max3_f32 v151, v151, v192, v198
	v_mul_f32_e32 v192, 0x3e38aa3b, v68
	v_mul_f32_e32 v198, 0x3e38aa3b, v69
	v_max3_f32 v151, v151, v192, v198
	v_mul_f32_e32 v192, 0x3e38aa3b, v70
	v_mul_f32_e32 v198, 0x3e38aa3b, v71
	v_max3_f32 v151, v151, v192, v198
	v_mul_f32_e32 v192, 0x3e38aa3b, v72
	v_mul_f32_e32 v198, 0x3e38aa3b, v73
	v_max3_f32 v151, v151, v192, v198
	v_mul_f32_e32 v192, 0x3e38aa3b, v74
	v_mul_f32_e32 v198, 0x3e38aa3b, v75
	v_max3_f32 v151, v151, v192, v198
	v_mul_f32_e32 v192, 0x3e38aa3b, v76
	v_mul_f32_e32 v198, 0x3e38aa3b, v77
	v_max3_f32 v151, v151, v192, v198
	v_mul_f32_e32 v192, 0x3e38aa3b, v78
	v_mul_f32_e32 v198, 0x3e38aa3b, v79
	v_max3_f32 v151, v151, v192, v198
	v_mul_f32_e32 v192, 0x3e38aa3b, v48
	v_mul_f32_e32 v198, 0x3e38aa3b, v49
	v_max3_f32 v151, v151, v192, v198
	v_mul_f32_e32 v192, 0x3e38aa3b, v50
	v_mul_f32_e32 v198, 0x3e38aa3b, v51
	v_max3_f32 v151, v151, v192, v198
	v_mul_f32_e32 v192, 0x3e38aa3b, v52
	v_mul_f32_e32 v198, 0x3e38aa3b, v53
	v_max3_f32 v151, v151, v192, v198
	v_mul_f32_e32 v192, 0x3e38aa3b, v54
	v_mul_f32_e32 v198, 0x3e38aa3b, v55
	v_max3_f32 v151, v151, v192, v198
	v_mul_f32_e32 v192, 0x3e38aa3b, v56
	v_mul_f32_e32 v198, 0x3e38aa3b, v57
	v_max3_f32 v151, v151, v192, v198
	v_mul_f32_e32 v192, 0x3e38aa3b, v58
	v_mul_f32_e32 v198, 0x3e38aa3b, v59
	v_max3_f32 v151, v151, v192, v198
	v_mul_f32_e32 v192, 0x3e38aa3b, v60
	v_mul_f32_e32 v198, 0x3e38aa3b, v61
	v_max3_f32 v151, v151, v192, v198
	v_mul_f32_e32 v192, 0x3e38aa3b, v62
	v_mul_f32_e32 v198, 0x3e38aa3b, v63
	v_max3_f32 v151, v151, v192, v198
	v_mul_f32_e32 v192, 0x3e38aa3b, v32
	v_mul_f32_e32 v198, 0x3e38aa3b, v33
	v_max3_f32 v151, v151, v192, v198
	v_mul_f32_e32 v192, 0x3e38aa3b, v34
	v_mul_f32_e32 v198, 0x3e38aa3b, v35
	v_max3_f32 v151, v151, v192, v198
	v_mul_f32_e32 v192, 0x3e38aa3b, v36
	v_mul_f32_e32 v198, 0x3e38aa3b, v37
	v_max3_f32 v151, v151, v192, v198
	v_mul_f32_e32 v192, 0x3e38aa3b, v38
	v_mul_f32_e32 v198, 0x3e38aa3b, v39
	v_max3_f32 v151, v151, v192, v198
	v_mul_f32_e32 v192, 0x3e38aa3b, v40
	v_mul_f32_e32 v198, 0x3e38aa3b, v41
	v_max3_f32 v151, v151, v192, v198
	v_mul_f32_e32 v192, 0x3e38aa3b, v42
	v_mul_f32_e32 v198, 0x3e38aa3b, v43
	v_max3_f32 v151, v151, v192, v198
	v_mul_f32_e32 v192, 0x3e38aa3b, v44
	v_mul_f32_e32 v198, 0x3e38aa3b, v45
	v_max3_f32 v151, v151, v192, v198
	v_mul_f32_e32 v192, 0x3e38aa3b, v46
	v_mul_f32_e32 v198, 0x3e38aa3b, v47
	v_max3_f32 v151, v151, v192, v198
	ds_bpermute_b32 v192, v148, v151
	s_waitcnt lgkmcnt(0)
	v_max_f32_e32 v192, v192, v192
	v_max_f32_e32 v151, v151, v192
	v_sub_f32_e32 v152, v152, v151
	v_fma_f32 v80, v80, s46, -v151
	v_exp_f32_e32 v152, v152
	v_exp_f32_e32 v154, v80
	v_fma_f32 v81, v81, s46, -v151
	v_fma_f32 v64, v64, s46, -v151
	v_pk_mul_f32 v[14:15], v[14:15], v[152:153] op_sel_hi:[1,0]
	v_pk_mul_f32 v[12:13], v[12:13], v[152:153] op_sel_hi:[1,0]
	v_pk_mul_f32 v[10:11], v[10:11], v[152:153] op_sel_hi:[1,0]
	v_pk_mul_f32 v[8:9], v[8:9], v[152:153] op_sel_hi:[1,0]
	v_pk_mul_f32 v[6:7], v[6:7], v[152:153] op_sel_hi:[1,0]
	v_pk_mul_f32 v[4:5], v[4:5], v[152:153] op_sel_hi:[1,0]
	v_pk_mul_f32 v[2:3], v[2:3], v[152:153] op_sel_hi:[1,0]
	v_pk_mul_f32 v[0:1], v[0:1], v[152:153] op_sel_hi:[1,0]
	v_pk_mul_f32 v[30:31], v[30:31], v[152:153] op_sel_hi:[1,0]
	v_pk_mul_f32 v[28:29], v[28:29], v[152:153] op_sel_hi:[1,0]
	v_pk_mul_f32 v[26:27], v[26:27], v[152:153] op_sel_hi:[1,0]
	v_pk_mul_f32 v[24:25], v[24:25], v[152:153] op_sel_hi:[1,0]
	v_pk_mul_f32 v[22:23], v[22:23], v[152:153] op_sel_hi:[1,0]
	v_pk_mul_f32 v[20:21], v[20:21], v[152:153] op_sel_hi:[1,0]
	v_pk_mul_f32 v[18:19], v[18:19], v[152:153] op_sel_hi:[1,0]
	v_pk_mul_f32 v[16:17], v[16:17], v[152:153] op_sel_hi:[1,0]
	v_fma_f32 v80, v153, v152, v154
	v_exp_f32_e32 v152, v81
	v_fma_f32 v81, v82, s46, -v151
	v_exp_f32_e32 v153, v81
	v_fma_f32 v81, v83, s46, -v151
	v_exp_f32_e32 v155, v81
	v_fma_f32 v81, v84, s46, -v151
	v_exp_f32_e32 v156, v81
	v_fma_f32 v81, v85, s46, -v151
	v_add_f32_e32 v80, v152, v80
	v_exp_f32_e32 v157, v81
	v_fma_f32 v81, v86, s46, -v151
	v_add_f32_e32 v80, v153, v80
	v_exp_f32_e32 v158, v81
	v_fma_f32 v81, v87, s46, -v151
	v_add_f32_e32 v80, v155, v80
	v_exp_f32_e32 v159, v81
	v_add_f32_e32 v80, v156, v80
	v_add_f32_e32 v80, v157, v80
	v_add_f32_e32 v80, v158, v80
	v_add_f32_e32 v81, v159, v80
	v_fma_f32 v80, v88, s46, -v151
	v_exp_f32_e32 v80, v80
	v_fma_f32 v83, v90, s46, -v151
	v_exp_f32_e32 v83, v83
	v_fma_f32 v84, v91, s46, -v151
	v_add_f32_e32 v82, v80, v81
	v_fma_f32 v81, v89, s46, -v151
	v_exp_f32_e32 v81, v81
	v_exp_f32_e32 v85, v84
	v_fma_f32 v84, v92, s46, -v151
	v_exp_f32_e32 v86, v84
	v_fma_f32 v84, v93, s46, -v151
	v_add_f32_e32 v82, v81, v82
	v_exp_f32_e32 v88, v84
	v_fma_f32 v84, v94, s46, -v151
	v_add_f32_e32 v82, v83, v82
	v_exp_f32_e32 v90, v84
	v_fma_f32 v84, v95, s46, -v151
	v_add_f32_e32 v82, v85, v82
	v_exp_f32_e32 v92, v84
	v_add_f32_e32 v82, v86, v82
	v_exp_f32_e32 v64, v64
	v_add_f32_e32 v82, v88, v82
	v_add_f32_e32 v82, v90, v82
	v_add_f32_e32 v82, v92, v82
	v_fma_f32 v65, v65, s46, -v151
	v_add_f32_e32 v84, v64, v82
	v_exp_f32_e32 v82, v65
	v_fma_f32 v66, v66, s46, -v151
	v_fma_f32 v48, v48, s46, -v151
	v_fma_f32 v49, v49, s46, -v151
	v_add_f32_e32 v65, v82, v84
	v_exp_f32_e32 v84, v66
	v_fma_f32 v66, v67, s46, -v151
	v_exp_f32_e32 v87, v66
	v_fma_f32 v66, v68, s46, -v151
	v_exp_f32_e32 v68, v66
	v_fma_f32 v66, v69, s46, -v151
	v_exp_f32_e32 v89, v66
	v_fma_f32 v66, v70, s46, -v151
	v_add_f32_e32 v65, v84, v65
	v_exp_f32_e32 v91, v66
	v_fma_f32 v66, v71, s46, -v151
	v_add_f32_e32 v65, v87, v65
	v_exp_f32_e32 v71, v66
	v_fma_f32 v66, v72, s46, -v151
	v_add_f32_e32 v65, v68, v65
	v_exp_f32_e32 v72, v66
	v_fma_f32 v66, v73, s46, -v151
	v_add_f32_e32 v65, v89, v65
	v_exp_f32_e32 v73, v66
	v_fma_f32 v66, v74, s46, -v151
	v_add_f32_e32 v65, v91, v65
	v_exp_f32_e32 v74, v66
	v_fma_f32 v66, v75, s46, -v151
	v_add_f32_e32 v65, v71, v65
	v_exp_f32_e32 v75, v66
	v_fma_f32 v66, v76, s46, -v151
	v_add_f32_e32 v65, v72, v65
	v_exp_f32_e32 v76, v66
	v_fma_f32 v66, v77, s46, -v151
	v_add_f32_e32 v65, v73, v65
	v_exp_f32_e32 v77, v66
	v_fma_f32 v66, v78, s46, -v151
	v_add_f32_e32 v65, v74, v65
	v_exp_f32_e32 v78, v66
	v_fma_f32 v66, v79, s46, -v151
	v_add_f32_e32 v65, v75, v65
	v_exp_f32_e32 v79, v66
	v_add_f32_e32 v65, v76, v65
	v_add_f32_e32 v65, v77, v65
	v_add_f32_e32 v65, v78, v65
	v_add_f32_e32 v66, v79, v65
	v_exp_f32_e32 v65, v48
	v_fma_f32 v32, v32, s46, -v151
	v_add_f32_e32 v48, v65, v66
	v_exp_f32_e32 v66, v49
	v_fma_f32 v49, v50, s46, -v151
	v_exp_f32_e32 v67, v49
	v_fma_f32 v49, v51, s46, -v151
	v_exp_f32_e32 v69, v49
	v_fma_f32 v49, v52, s46, -v151
	v_exp_f32_e32 v70, v49
	v_fma_f32 v49, v53, s46, -v151
	v_exp_f32_e32 v53, v49
	v_fma_f32 v49, v54, s46, -v151
	v_exp_f32_e32 v54, v49
	v_fma_f32 v49, v55, s46, -v151
	v_exp_f32_e32 v55, v49
	v_fma_f32 v49, v56, s46, -v151
	v_exp_f32_e32 v56, v49
	v_fma_f32 v49, v57, s46, -v151
	v_exp_f32_e32 v57, v49
	v_fma_f32 v49, v58, s46, -v151
	v_exp_f32_e32 v58, v49
	v_fma_f32 v49, v59, s46, -v151
	v_exp_f32_e32 v59, v49
	v_fma_f32 v49, v60, s46, -v151
	v_exp_f32_e32 v60, v49
	v_fma_f32 v49, v61, s46, -v151
	v_exp_f32_e32 v61, v49
	v_fma_f32 v49, v62, s46, -v151
	v_exp_f32_e32 v62, v49
	v_fma_f32 v49, v63, s46, -v151
	v_exp_f32_e32 v63, v49
	v_exp_f32_e32 v49, v32
	v_fma_f32 v32, v33, s46, -v151
	v_exp_f32_e32 v50, v32
	v_fma_f32 v32, v34, s46, -v151
	v_exp_f32_e32 v51, v32
	v_fma_f32 v32, v35, s46, -v151
	v_exp_f32_e32 v52, v32
	v_fma_f32 v32, v36, s46, -v151
	v_exp_f32_e32 v36, v32
	v_fma_f32 v32, v37, s46, -v151
	v_exp_f32_e32 v37, v32
	v_fma_f32 v32, v38, s46, -v151
	v_exp_f32_e32 v38, v32
	v_fma_f32 v32, v39, s46, -v151
	v_exp_f32_e32 v39, v32
	v_fma_f32 v32, v40, s46, -v151
	v_exp_f32_e32 v40, v32
	v_fma_f32 v32, v41, s46, -v151
	v_exp_f32_e32 v41, v32
	v_fma_f32 v32, v42, s46, -v151
	v_exp_f32_e32 v42, v32
	v_fma_f32 v32, v43, s46, -v151
	v_exp_f32_e32 v43, v32
	v_fma_f32 v32, v44, s46, -v151
	v_exp_f32_e32 v44, v32
	v_fma_f32 v32, v45, s46, -v151
	v_exp_f32_e32 v45, v32
	v_fma_f32 v32, v46, s46, -v151
	v_exp_f32_e32 v46, v32
	v_fma_f32 v32, v47, s46, -v151
	v_exp_f32_e32 v47, v32
	v_cvt_pk_bf16_f32 v32, v154, v152
	v_cvt_pk_bf16_f32 v33, v153, v155
	ds_read_b64_tr_b16 v[152:153], v150 offset:61440
	ds_read_b64_tr_b16 v[154:155], v150 offset:62976
	v_cvt_pk_bf16_f32 v34, v156, v157
	v_cvt_pk_bf16_f32 v35, v158, v159
	v_add_f32_e32 v48, v66, v48
	v_add_f32_e32 v48, v67, v48
	s_waitcnt lgkmcnt(0)
	v_mfma_f32_32x32x16_bf16 v[16:31], v[152:155], v[32:35], v[16:31]
	ds_read_b64_tr_b16 v[152:153], v150 offset:61504
	ds_read_b64_tr_b16 v[154:155], v150 offset:63040
	v_add_f32_e32 v48, v69, v48
	v_add_f32_e32 v48, v70, v48
	v_add_f32_e32 v48, v53, v48
	v_add_f32_e32 v48, v54, v48
	v_add_f32_e32 v48, v55, v48
	v_add_f32_e32 v48, v56, v48
	s_waitcnt lgkmcnt(0)
	v_mfma_f32_32x32x16_bf16 v[0:15], v[152:155], v[32:35], v[0:15]
	v_cvt_pk_bf16_f32 v35, v90, v92
	ds_read_b64_tr_b16 v[92:93], v150 offset:64512
	ds_read_b64_tr_b16 v[94:95], v149 offset:29184
	v_cvt_pk_bf16_f32 v32, v80, v81
	v_cvt_pk_bf16_f32 v33, v83, v85
	v_cvt_pk_bf16_f32 v34, v86, v88
	v_add_f32_e32 v48, v57, v48
	v_add_f32_e32 v48, v58, v48
	s_waitcnt lgkmcnt(0)
	v_mfma_f32_32x32x16_bf16 v[16:31], v[92:95], v[32:35], v[16:31]
	ds_read_b64_tr_b16 v[92:93], v150 offset:64576
	ds_read_b64_tr_b16 v[94:95], v149 offset:29248
	v_add_f32_e32 v48, v59, v48
	v_add_f32_e32 v48, v60, v48
	v_add_f32_e32 v48, v61, v48
	v_add_f32_e32 v48, v62, v48
	v_add_f32_e32 v48, v63, v48
	s_waitcnt lgkmcnt(0)
	v_mfma_f32_32x32x16_bf16 v[0:15], v[92:95], v[32:35], v[0:15]
	v_cvt_pk_bf16_f32 v32, v64, v82
	ds_read_b64_tr_b16 v[80:81], v149 offset:30720
	ds_read_b64_tr_b16 v[82:83], v149 offset:32256
	v_cvt_pk_bf16_f32 v33, v84, v87
	v_cvt_pk_bf16_f32 v34, v68, v89
	v_cvt_pk_bf16_f32 v35, v91, v71
	s_waitcnt lgkmcnt(0)
	s_nop 0
	v_mfma_f32_32x32x16_bf16 v[16:31], v[80:83], v[32:35], v[16:31]
	ds_read_b64_tr_b16 v[80:81], v149 offset:30784
	ds_read_b64_tr_b16 v[82:83], v149 offset:32320
	s_waitcnt lgkmcnt(0)
	v_mfma_f32_32x32x16_bf16 v[0:15], v[80:83], v[32:35], v[0:15]
	v_cvt_pk_bf16_f32 v32, v72, v73
	v_cvt_pk_bf16_f32 v33, v74, v75
	ds_read_b64_tr_b16 v[72:73], v149 offset:33792
	ds_read_b64_tr_b16 v[74:75], v149 offset:35328
	v_cvt_pk_bf16_f32 v34, v76, v77
	v_cvt_pk_bf16_f32 v35, v78, v79
	s_waitcnt lgkmcnt(0)
	s_nop 0
	v_mfma_f32_32x32x16_bf16 v[16:31], v[72:75], v[32:35], v[16:31]
	ds_read_b64_tr_b16 v[72:73], v149 offset:33856
	ds_read_b64_tr_b16 v[74:75], v149 offset:35392
	s_waitcnt lgkmcnt(0)
	v_mfma_f32_32x32x16_bf16 v[0:15], v[72:75], v[32:35], v[0:15]
	v_cvt_pk_bf16_f32 v32, v65, v66
	v_cvt_pk_bf16_f32 v33, v67, v69
	ds_read_b64_tr_b16 v[64:65], v149 offset:36864
	ds_read_b64_tr_b16 v[66:67], v149 offset:38400
	v_cvt_pk_bf16_f32 v34, v70, v53
	v_cvt_pk_bf16_f32 v35, v54, v55
	s_waitcnt lgkmcnt(0)
	s_nop 0
	v_mfma_f32_32x32x16_bf16 v[16:31], v[64:67], v[32:35], v[16:31]
	ds_read_b64_tr_b16 v[64:65], v149 offset:36928
	ds_read_b64_tr_b16 v[66:67], v149 offset:38464
	s_waitcnt lgkmcnt(0)
	v_mfma_f32_32x32x16_bf16 v[0:15], v[64:67], v[32:35], v[0:15]
	v_cvt_pk_bf16_f32 v32, v56, v57
	ds_read_b64_tr_b16 v[54:55], v149 offset:39936
	ds_read_b64_tr_b16 v[56:57], v149 offset:41472
	v_cvt_pk_bf16_f32 v33, v58, v59
	v_cvt_pk_bf16_f32 v34, v60, v61
	v_cvt_pk_bf16_f32 v35, v62, v63
	s_waitcnt lgkmcnt(0)
	s_nop 0
	v_mfma_f32_32x32x16_bf16 v[16:31], v[54:57], v[32:35], v[16:31]
	ds_read_b64_tr_b16 v[54:55], v149 offset:40000
	ds_read_b64_tr_b16 v[56:57], v149 offset:41536
	s_waitcnt lgkmcnt(0)
	v_mfma_f32_32x32x16_bf16 v[0:15], v[54:57], v[32:35], v[0:15]
	ds_read_b64_tr_b16 v[54:55], v149 offset:43008
	ds_read_b64_tr_b16 v[56:57], v149 offset:44544
	v_cvt_pk_bf16_f32 v32, v49, v50
	v_cvt_pk_bf16_f32 v33, v51, v52
	v_cvt_pk_bf16_f32 v34, v36, v37
	v_cvt_pk_bf16_f32 v35, v38, v39
	s_waitcnt lgkmcnt(0)
	s_nop 0
	v_mfma_f32_32x32x16_bf16 v[16:31], v[54:57], v[32:35], v[16:31]
	ds_read_b64_tr_b16 v[54:55], v149 offset:43072
	ds_read_b64_tr_b16 v[56:57], v149 offset:44608
	s_waitcnt lgkmcnt(0)
	v_mfma_f32_32x32x16_bf16 v[0:15], v[54:57], v[32:35], v[0:15]
	ds_read_b64_tr_b16 v[54:55], v149 offset:46080
	ds_read_b64_tr_b16 v[56:57], v149 offset:47616
	v_cvt_pk_bf16_f32 v32, v40, v41
	v_cvt_pk_bf16_f32 v33, v42, v43
	v_cvt_pk_bf16_f32 v34, v44, v45
	v_cvt_pk_bf16_f32 v35, v46, v47
	s_waitcnt lgkmcnt(0)
	s_nop 0
	v_mfma_f32_32x32x16_bf16 v[16:31], v[54:57], v[32:35], v[16:31]
	ds_read_b64_tr_b16 v[54:55], v149 offset:46144
	ds_read_b64_tr_b16 v[56:57], v149 offset:47680
	s_waitcnt lgkmcnt(0)
	v_mfma_f32_32x32x16_bf16 v[0:15], v[54:57], v[32:35], v[0:15]
	v_add_f32_e32 v32, v49, v48
	v_add_f32_e32 v32, v50, v32
	v_add_f32_e32 v32, v51, v32
	v_add_f32_e32 v32, v52, v32
	v_add_f32_e32 v32, v36, v32
	v_add_f32_e32 v32, v37, v32
	v_add_f32_e32 v32, v38, v32
	v_add_f32_e32 v32, v39, v32
	v_add_f32_e32 v32, v40, v32
	v_add_f32_e32 v32, v41, v32
	v_add_f32_e32 v32, v42, v32
	v_add_f32_e32 v32, v43, v32
	v_add_f32_e32 v32, v44, v32
	v_add_f32_e32 v32, v45, v32
	v_add_f32_e32 v32, v46, v32
	v_add_f32_e32 v32, v47, v32
	ds_bpermute_b32 v33, v148, v32
	s_waitcnt lgkmcnt(0)
	v_add_f32_e32 v32, v32, v33
	v_div_scale_f32 v33, s[0:1], v32, v32, 1.0
	v_rcp_f32_e32 v34, v33
	s_nop 0
	v_fma_f32 v35, -v33, v34, 1.0
	v_fmac_f32_e32 v34, v35, v34
	v_div_scale_f32 v35, vcc, 1.0, v32, 1.0
	v_mul_f32_e32 v36, v35, v34
	v_fma_f32 v37, -v33, v36, v35
	v_fmac_f32_e32 v36, v37, v34
	v_fma_f32 v33, -v33, v36, v35
	v_div_fmas_f32 v33, v33, v34, v36
	v_div_fixup_f32 v32, v33, v32, 1.0
	v_lshl_add_u64 v[34:35], v[144:145], 0, v[194:195]
	v_pk_mul_f32 v[16:17], v[16:17], v[32:33] op_sel_hi:[1,0]
	v_pk_mul_f32 v[18:19], v[18:19], v[32:33] op_sel_hi:[1,0]
	v_pk_mul_f32 v[20:21], v[20:21], v[32:33] op_sel_hi:[1,0]
	v_pk_mul_f32 v[22:23], v[22:23], v[32:33] op_sel_hi:[1,0]
	v_pk_mul_f32 v[24:25], v[24:25], v[32:33] op_sel_hi:[1,0]
	v_pk_mul_f32 v[26:27], v[26:27], v[32:33] op_sel_hi:[1,0]
	v_pk_mul_f32 v[28:29], v[28:29], v[32:33] op_sel_hi:[1,0]
	v_pk_mul_f32 v[30:31], v[30:31], v[32:33] op_sel_hi:[1,0]
	v_pk_mul_f32 v[0:1], v[0:1], v[32:33] op_sel_hi:[1,0]
	v_pk_mul_f32 v[2:3], v[2:3], v[32:33] op_sel_hi:[1,0]
	v_pk_mul_f32 v[4:5], v[4:5], v[32:33] op_sel_hi:[1,0]
	v_pk_mul_f32 v[6:7], v[6:7], v[32:33] op_sel_hi:[1,0]
	v_pk_mul_f32 v[8:9], v[8:9], v[32:33] op_sel_hi:[1,0]
	v_pk_mul_f32 v[10:11], v[10:11], v[32:33] op_sel_hi:[1,0]
	v_pk_mul_f32 v[12:13], v[12:13], v[32:33] op_sel_hi:[1,0]
	v_pk_mul_f32 v[14:15], v[14:15], v[32:33] op_sel_hi:[1,0]
	v_mbcnt_lo_u32_b32 v36, -1, 0
	v_mbcnt_hi_u32_b32 v36, -1, v36
	v_and_b32_e32 v36, 32, v36
	v_lshrrev_b32_e32 v36, 2, v36
	v_mov_b32_e32 v37, 0
	v_lshl_add_u64 v[34:35], v[34:35], 0, v[36:37]
	v_cvt_pk_bf16_f32 v0, v0, v1
	v_cvt_pk_bf16_f32 v1, v2, v3
	v_cvt_pk_bf16_f32 v2, v4, v5
	v_cvt_pk_bf16_f32 v3, v6, v7
	v_cvt_pk_bf16_f32 v4, v8, v9
	v_cvt_pk_bf16_f32 v5, v10, v11
	v_cvt_pk_bf16_f32 v6, v12, v13
	v_cvt_pk_bf16_f32 v7, v14, v15
	v_cvt_pk_bf16_f32 v8, v16, v17
	v_cvt_pk_bf16_f32 v9, v18, v19
	v_cvt_pk_bf16_f32 v10, v20, v21
	v_cvt_pk_bf16_f32 v11, v22, v23
	v_cvt_pk_bf16_f32 v12, v24, v25
	v_cvt_pk_bf16_f32 v13, v26, v27
	v_cvt_pk_bf16_f32 v14, v28, v29
	v_cvt_pk_bf16_f32 v15, v30, v31
	s_nop 1
	v_permlane32_swap_b32_e32 v0, v2
	v_permlane32_swap_b32_e32 v1, v3
	v_permlane32_swap_b32_e32 v4, v6
	v_permlane32_swap_b32_e32 v5, v7
	v_permlane32_swap_b32_e32 v8, v10
	v_permlane32_swap_b32_e32 v9, v11
	v_permlane32_swap_b32_e32 v12, v14
	v_permlane32_swap_b32_e32 v13, v15
	global_store_dwordx4 v[34:35], v[8:11], off
	global_store_dwordx4 v[34:35], v[12:15], off offset:32
	global_store_dwordx4 v[34:35], v[0:3], off offset:64
	global_store_dwordx4 v[34:35], v[4:7], off offset:96
	s_branch .LBB0_952
